# P0 x->bf16 rows: the eight row loads of an iteration issued together (counted wait for the first four) instead of two dependent batches
# baseline (speedup 1.0000x reference)
; __global__ void __launch_bounds__(512, 2) fwd_mega(Args args) {
;     ...
;         for (int m = 2 * gw; m < T; m += 2 * ngw) {
;             const f32x4* x0 = (const f32x4*)(x + (size_t)m * DM) + lane; const f32x4* x1 = x0 + DM / 4;
;             f32x4 v0[4], v1[4]; float s0 = 0.f, s1 = 0.f;
; #pragma unroll
;             for (int jj = 0; jj < 4; ++jj) { v0[jj] = x0[64 * jj]; v1[jj] = x1[64 * jj]; }
; #pragma unroll
;             for (int jj = 0; jj < 4; ++jj) { s0 += (v0[jj][0] * v0[jj][0] + v0[jj][1] * v0[jj][1]) + (v0[jj][2] * v0[jj][2] + v0[jj][3] * v0[jj][3]);
;                                              s1 += (v1[jj][0] * v1[jj][0] + v1[jj][1] * v1[jj][1]) + (v1[jj][2] * v1[jj][2] + v1[jj][3] * v1[jj][3]); }
;             const float q0_ = sqrtf(wave_sum(s0) * (1.0f / 1024.0f) + EPS), q1_ = sqrtf(wave_sum(s1) * (1.0f / 1024.0f) + EPS), r0 = 1.0f / q0_, r1 = 1.0f / q1_;
;             if (lane == 0) { ((float*)(ws + S_R0))[m] = q0_; ((float*)(ws + S_R0))[m + 1] = q1_; }
;     ...
;         for (int m = gw; m < 512; m += ngw) rms_row_to_bf16(mem + (size_t)m * DM, args.in[19], MEMN + (size_t)m * DM, lane);
.LBB0_237:
	global_load_dwordx4 v[24:27], v[36:37], off offset:-3072
	global_load_dwordx4 v[12:15], v[36:37], off offset:-2048
	global_load_dwordx4 v[4:7], v[36:37], off offset:-1024
	global_load_dwordx4 v[0:3], v[36:37], off
	v_add_co_u32_e32 v8, vcc, 0xfffff000, v36
	s_nop 1
	v_addc_co_u32_e32 v9, vcc, -1, v37, vcc
	global_load_dwordx4 v[28:31], v[8:9], off offset:-3072
	global_load_dwordx4 v[20:23], v[8:9], off offset:-2048
	global_load_dwordx4 v[16:19], v[8:9], off offset:-1024
	s_nop 0
	global_load_dwordx4 v[8:11], v[36:37], off offset:-4096
	s_waitcnt vmcnt(4)
	v_mul_f32_e32 v38, v25, v25
	v_mul_f32_e32 v39, v27, v27
	v_mul_f32_e32 v47, v13, v13
	v_mul_f32_e32 v48, v15, v15
	v_mul_f32_e32 v49, v5, v5
	v_mul_f32_e32 v50, v7, v7
	v_fmac_f32_e32 v38, v24, v24
	v_fmac_f32_e32 v39, v26, v26
	v_fmac_f32_e32 v47, v12, v12
	v_fmac_f32_e32 v48, v14, v14
	v_mul_f32_e32 v51, v1, v1
	v_mul_f32_e32 v52, v3, v3
	v_fmac_f32_e32 v49, v4, v4
	v_fmac_f32_e32 v50, v6, v6
	v_add_f32_e32 v38, v38, v39
	v_add_f32_e32 v47, v47, v48
	v_fmac_f32_e32 v51, v0, v0
	v_fmac_f32_e32 v52, v2, v2
	v_add_f32_e32 v49, v49, v50
	v_add_f32_e32 v38, v38, v47
	v_add_f32_e32 v51, v51, v52
	v_add_f32_e32 v38, v38, v49
	v_add_f32_e32 v38, v38, v51
	s_waitcnt vmcnt(0)
	v_mul_f32_e32 v53, v29, v29
	v_mul_f32_e32 v54, v31, v31
	v_mul_f32_e32 v39, v21, v21
	v_mul_f32_e32 v55, v23, v23
	v_mul_f32_e32 v48, v17, v17
	v_mul_f32_e32 v56, v19, v19
	v_fmac_f32_e32 v53, v28, v28
	v_fmac_f32_e32 v54, v30, v30
	v_fmac_f32_e32 v39, v20, v20
	v_fmac_f32_e32 v55, v22, v22
	v_mul_f32_e32 v50, v9, v9
	v_mul_f32_e32 v57, v11, v11
	v_fmac_f32_e32 v48, v16, v16
	v_fmac_f32_e32 v56, v18, v18
	v_add_f32_e32 v47, v53, v54
	v_add_f32_e32 v39, v39, v55
	v_fmac_f32_e32 v50, v8, v8
	v_fmac_f32_e32 v57, v10, v10
	v_add_f32_e32 v48, v48, v56
	v_add_f32_e32 v39, v47, v39
	v_add_f32_e32 v49, v50, v57
	v_add_f32_e32 v39, v39, v48
	ds_bpermute_b32 v47, v40, v38
	v_add_f32_e32 v39, v39, v49
	ds_bpermute_b32 v48, v40, v39
	s_waitcnt lgkmcnt(0)
	v_add_f32_e32 v38, v38, v47
	ds_bpermute_b32 v47, v41, v38
	v_add_f32_e32 v39, v39, v48
	ds_bpermute_b32 v48, v41, v39
	s_waitcnt lgkmcnt(1)
	v_add_f32_e32 v38, v38, v47
	ds_bpermute_b32 v47, v42, v38
	s_waitcnt lgkmcnt(1)
	v_add_f32_e32 v39, v39, v48
	ds_bpermute_b32 v48, v42, v39
	s_waitcnt lgkmcnt(1)
	v_add_f32_e32 v38, v38, v47
	ds_bpermute_b32 v47, v43, v38
	s_waitcnt lgkmcnt(1)
	v_add_f32_e32 v39, v39, v48
	ds_bpermute_b32 v48, v43, v39
	s_waitcnt lgkmcnt(1)
	v_add_f32_e32 v38, v38, v47
	ds_bpermute_b32 v47, v44, v38
	s_waitcnt lgkmcnt(1)
	v_add_f32_e32 v39, v39, v48
	ds_bpermute_b32 v48, v44, v39
	s_waitcnt lgkmcnt(1)
	v_add_f32_e32 v38, v38, v47
	ds_bpermute_b32 v47, v45, v38
	s_waitcnt lgkmcnt(1)
	v_add_f32_e32 v39, v39, v48
	ds_bpermute_b32 v48, v45, v39
	s_waitcnt lgkmcnt(1)
	v_add_f32_e32 v38, v38, v47
	v_fmamk_f32 v38, v38, 0x3a800000, v33
	s_waitcnt lgkmcnt(0)
	v_add_f32_e32 v39, v39, v48
	v_mul_f32_e32 v47, 0x4f800000, v38
	v_cmp_gt_f32_e32 vcc, s12, v38
	v_fmamk_f32 v39, v39, 0x3a800000, v33
	v_cmp_gt_f32_e64 s[4:5], s12, v39
	v_cndmask_b32_e32 v47, v38, v47, vcc
	v_mul_f32_e32 v38, 0x4f800000, v39
	v_sqrt_f32_e32 v48, v47
	v_cndmask_b32_e64 v38, v39, v38, s[4:5]
	v_sqrt_f32_e32 v39, v38
	v_add_u32_e32 v49, -1, v48
	v_add_u32_e32 v50, 1, v48
	v_fma_f32 v51, -v49, v48, v47
	v_fma_f32 v52, -v50, v48, v47
	v_add_u32_e32 v53, -1, v39
	v_cmp_ge_f32_e64 s[6:7], 0, v51
	v_add_u32_e32 v54, 1, v39
	v_fma_f32 v51, -v54, v39, v38
	v_cndmask_b32_e64 v48, v48, v49, s[6:7]
	v_fma_f32 v49, -v53, v39, v38
	v_cmp_lt_f32_e64 s[6:7], 0, v52
	s_nop 1
	v_cndmask_b32_e64 v48, v48, v50, s[6:7]
	v_cmp_ge_f32_e64 s[6:7], 0, v49
	v_mul_f32_e32 v49, 0x37800000, v48
	v_cndmask_b32_e32 v48, v48, v49, vcc
	v_cndmask_b32_e64 v39, v39, v53, s[6:7]
	v_cmp_lt_f32_e64 s[6:7], 0, v51
	v_cmp_class_f32_e32 vcc, v38, v46
	s_nop 0
	v_cndmask_b32_e64 v39, v39, v54, s[6:7]
	v_mul_f32_e32 v49, 0x37800000, v39
	v_cndmask_b32_e64 v39, v39, v49, s[4:5]
	v_cndmask_b32_e32 v38, v39, v38, vcc
	v_cmp_class_f32_e32 vcc, v47, v46
	s_nop 1
	v_cndmask_b32_e32 v39, v48, v47, vcc
	s_and_saveexec_b64 s[4:5], s[2:3]
	s_cbranch_execz .LBB0_236
	s_add_u32 s6, s8, s74
	s_addc_u32 s7, s9, s75
	v_mov_b32_e32 v47, s6
	v_add_co_u32_e32 v48, vcc, 0x3560000, v47
	v_mov_b32_e32 v47, s7
	s_nop 0
	v_addc_co_u32_e32 v49, vcc, 0, v47, vcc
	flat_store_dwordx2 v[48:49], v[38:39]
	s_branch .LBB0_236
.LBB0_239:
	s_nop 0
	s_nop 0
	s_nop 0
	s_nop 0
	s_nop 0
	s_nop 0
	s_nop 0
	v_readlane_b32 s98, v249, 54
	s_add_i32 s100, s98, 0xfffffb00
	s_and_b32 s100, s100, 0x7ff
	s_cmpk_eq_i32 s86, 0x100
	s_cselect_b32 s100, s100, s98
	s_cmpk_gt_i32 s100, 0x1ff
	s_cbranch_scc1 .LBB0_250
	v_mbcnt_lo_u32_b32 v0, -1, 0
	v_mbcnt_hi_u32_b32 v0, -1, v0
	v_and_b32_e32 v1, 64, v0
	v_add_u32_e32 v1, 64, v1
	v_xor_b32_e32 v2, 1, v0
	v_cmp_lt_i32_e32 vcc, v2, v1
	s_cmp_lg_u64 s[58:59], 0
	v_readlane_b32 s4, v249, 54
	v_cndmask_b32_e32 v2, v0, v2, vcc
	v_lshlrev_b32_e32 v30, 2, v2
	v_xor_b32_e32 v2, 2, v0
	v_cmp_lt_i32_e32 vcc, v2, v1
	s_cselect_b64 s[2:3], -1, 0
	v_readlane_b32 s5, v249, 55
	v_cndmask_b32_e32 v2, v0, v2, vcc
	v_lshlrev_b32_e32 v31, 2, v2
	v_xor_b32_e32 v2, 4, v0
	v_cmp_lt_i32_e32 vcc, v2, v1
	s_mov_b32 s14, s100
	s_ashr_i32 s15, s100, 31
	v_cndmask_b32_e32 v2, v0, v2, vcc
	v_lshlrev_b32_e32 v34, 2, v2
	v_xor_b32_e32 v2, 8, v0
	v_cmp_lt_i32_e32 vcc, v2, v1
	s_lshl_b64 s[4:5], s[14:15], 11
	v_mov_b32_e32 v33, 0
	v_cndmask_b32_e32 v2, v0, v2, vcc
	v_lshlrev_b32_e32 v35, 2, v2
	v_xor_b32_e32 v2, 16, v0
	v_cmp_lt_i32_e32 vcc, v2, v1
	s_add_u32 s4, s8, s4
	s_addc_u32 s5, s9, s5
	v_cndmask_b32_e32 v2, v0, v2, vcc
	v_lshlrev_b32_e32 v36, 2, v2
	v_xor_b32_e32 v2, 32, v0
	v_cmp_lt_i32_e32 vcc, v2, v1
	v_mov_b32_e32 v1, v33
	s_ashr_i32 s89, s88, 31
	v_cndmask_b32_e32 v0, v0, v2, vcc
	v_lshlrev_b32_e32 v37, 2, v0
	v_lshlrev_b32_e32 v0, 3, v128
	v_lshl_add_u64 v[0:1], s[4:5], 0, v[0:1]
	s_mov_b64 s[4:5], 0x3f00000
	v_readlane_b32 s36, v249, 17
	v_lshl_add_u64 v[24:25], v[0:1], 0, s[4:5]
	s_lshl_b64 s[6:7], s[88:89], 11
	s_lshl_b64 s[4:5], s[14:15], 12
	v_readlane_b32 s38, v249, 19
	v_readlane_b32 s39, v249, 20
	s_add_u32 s4, s38, s4
	s_addc_u32 s5, s39, s5
	v_lshl_add_u64 v[0:1], s[4:5], 0, v[32:33]
	s_mov_b64 s[4:5], 0x800
	v_lshl_add_u64 v[26:27], v[0:1], 0, s[4:5]
	v_cndmask_b32_e64 v0, 0, 1, s[2:3]
	s_mov_b32 s4, s98
	v_lshl_add_u64 v[22:23], s[58:59], 0, v[32:33]
	v_readlane_b32 s37, v249, 18
	v_readlane_b32 s40, v249, 21
	v_readlane_b32 s41, v249, 22
	v_readlane_b32 s42, v249, 23
	v_readlane_b32 s43, v249, 24
	v_readlane_b32 s44, v249, 25
	v_readlane_b32 s45, v249, 26
	v_readlane_b32 s46, v249, 27
	v_readlane_b32 s47, v249, 28
	v_readlane_b32 s48, v249, 29
	v_readlane_b32 s49, v249, 30
	v_readlane_b32 s50, v249, 31
	v_readlane_b32 s51, v249, 32
	s_lshl_b64 s[10:11], s[88:89], 12
	v_cmp_ne_u32_e64 s[2:3], 1, v0
	v_mov_b32_e32 v32, 0x358637bd
	s_mov_b32 s12, 0xf800000
	v_mov_b32_e32 v33, 0x260
	v_writelane_b32 v249, s4, 54
	s_mov_b32 s13, s14
	s_nop 0
	v_writelane_b32 v249, s5, 55
	s_branch .LBB0_242
